# as previous but NSA_QB table keeps one unit per size quartile per round (234/274)
# speedup vs baseline: 1.0063x; 1.0063x over previous
_ZL6NSA_QB:
	.byte	119, 65, 32, 18, 103, 82, 42, 7, 126, 75, 33, 0, 96, 78, 58, 2, 112, 67, 43, 12, 107, 86, 39, 1, 108, 66, 40, 20, 102, 83, 44, 6, 97, 77, 34, 25, 101, 72, 51, 11, 109, 73, 38, 14, 111, 79, 41, 3, 98, 70, 50, 17, 104, 74, 37, 19, 124, 69, 36, 5, 100, 68, 45, 22, 105, 87, 55, 27, 121, 85, 53, 15, 120, 89, 56, 9, 99, 92, 61, 21, 110, 94, 62, 8, 116, 71, 57, 30, 106, 76, 63, 29, 114, 88, 46, 26, 118, 93, 59, 4, 113, 90, 47, 24, 127, 64, 52, 31, 115, 95, 48, 16, 117, 80, 49, 28, 122, 81, 60, 10, 123, 84, 54, 13, 125, 91, 35, 23
	.size	_ZL6NSA_QB, 128

	.type	__hip_cuid_aaa9f4bcd633d1df,@object
